# v23 + attention QK MFMA groups reordered accumulator-adjacent (p0,p0,p1,p1)
# speedup vs baseline: 1.0086x; 1.0003x over previous
.LBB0_921:
	s_add_i32 s4, s33, 0xc000
	s_and_b32 s4, s4, 0xc000
	s_add_i32 s12, s4, 0
	s_add_i32 s12, s12, 0x10000
	v_add_u32_e32 v76, s12, v152
	v_add_u32_e32 v77, v76, v153
	ds_read_b128 v[68:71], v77 offset:0
	ds_read_b128 v[72:75], v77 offset:0x2000
	v_add_u32_e32 v77, v76, v155
	ds_read_b128 v[116:119], v77 offset:0
	ds_read_b128 v[120:123], v77 offset:0x2000
	v_add_u32_e32 v77, v76, v156
	ds_read_b128 v[124:127], v77 offset:0
	ds_read_b128 v[128:131], v77 offset:0x2000
	v_add_u32_e32 v76, v76, v157
	ds_read_b128 v[132:135], v76 offset:0
	ds_read_b128 v[136:139], v76 offset:0x2000
	s_waitcnt lgkmcnt(4)
	s_add_i32 s3, s2, 0xff
	s_cmp_le_u32 s3, s86
	v_mfma_f32_32x32x16_bf16 v[84:99], v[68:71], v[100:103], 0
	v_mfma_f32_32x32x16_bf16 v[84:99], v[116:119], v[104:107], v[84:99]
	v_mfma_f32_32x32x16_bf16 v[68:83], v[72:75], v[100:103], 0
	v_mfma_f32_32x32x16_bf16 v[68:83], v[120:123], v[104:107], v[68:83]
	s_waitcnt lgkmcnt(0)
	v_mfma_f32_32x32x16_bf16 v[84:99], v[124:127], v[108:111], v[84:99]
	v_mfma_f32_32x32x16_bf16 v[84:99], v[132:135], v[112:115], v[84:99]
	v_mfma_f32_32x32x16_bf16 v[68:83], v[128:131], v[108:111], v[68:83]
	v_mfma_f32_32x32x16_bf16 v[68:83], v[136:139], v[112:115], v[68:83]
	v_add_u32_e32 v162, s4, v158
	ds_read_b64_tr_b16 v[144:145], v162 offset:0
	ds_read_b64_tr_b16 v[146:147], v162 offset:0x800
	ds_read_b64_tr_b16 v[140:141], v162 offset:0x1000
	ds_read_b64_tr_b16 v[142:143], v162 offset:0x1800
	ds_read_b64_tr_b16 v[136:137], v162 offset:0x2000
	ds_read_b64_tr_b16 v[138:139], v162 offset:0x2800
	ds_read_b64_tr_b16 v[132:133], v162 offset:0x3000
	ds_read_b64_tr_b16 v[134:135], v162 offset:0x3800
	ds_read_b64_tr_b16 v[128:129], v162 offset:0x200
	ds_read_b64_tr_b16 v[130:131], v162 offset:0xa00
	ds_read_b64_tr_b16 v[124:125], v162 offset:0x1200
	ds_read_b64_tr_b16 v[126:127], v162 offset:0x1a00
	ds_read_b64_tr_b16 v[120:121], v162 offset:0x2200
	ds_read_b64_tr_b16 v[122:123], v162 offset:0x2a00
	ds_read_b64_tr_b16 v[116:117], v162 offset:0x3200
	ds_read_b64_tr_b16 v[118:119], v162 offset:0x3a00
	s_cbranch_scc1 .LBB0_923
	v_cmp_gt_i32_e64 s[70:71], 22, v159
	v_cmp_gt_i32_e64 s[72:73], 23, v159
	v_cmp_gt_i32_e64 s[68:69], 21, v159
	s_and_b64 s[70:71], s[72:73], s[70:71]
	v_cmp_gt_i32_e64 s[66:67], 20, v159
	s_and_b64 s[68:69], s[70:71], s[68:69]
	v_cmp_gt_i32_e64 s[64:65], 19, v159
	s_and_b64 s[66:67], s[68:69], s[66:67]
	v_cmp_gt_i32_e64 s[62:63], 18, v159
	s_and_b64 s[64:65], s[66:67], s[64:65]
	v_cmp_gt_i32_e64 s[60:61], 17, v159
	s_and_b64 s[62:63], s[64:65], s[62:63]
	v_cmp_gt_i32_e64 s[58:59], 16, v159
	s_and_b64 s[60:61], s[62:63], s[60:61]
	v_cmp_gt_i32_e64 s[56:57], 7, v159
	s_and_b64 s[58:59], s[60:61], s[58:59]
	v_cmp_gt_i32_e64 s[54:55], 6, v159
	s_and_b64 s[56:57], s[58:59], s[56:57]
	v_cmp_gt_i32_e64 s[52:53], 5, v159
	s_and_b64 s[54:55], s[56:57], s[54:55]
	v_cmp_gt_i32_e64 s[50:51], 4, v159
	s_and_b64 s[52:53], s[54:55], s[52:53]
	v_cmp_gt_i32_e64 s[48:49], 3, v159
	s_and_b64 s[50:51], s[52:53], s[50:51]
	v_cmp_gt_i32_e64 s[46:47], 2, v159
	s_and_b64 s[48:49], s[50:51], s[48:49]
	v_cmp_gt_i32_e64 s[44:45], 1, v159
	s_and_b64 s[46:47], s[48:49], s[46:47]
	v_cmp_gt_i32_e64 s[42:43], 0, v159
	s_and_b64 s[44:45], s[46:47], s[44:45]
	s_and_b64 s[42:43], s[44:45], s[42:43]
	v_cmp_gt_i32_e64 s[40:41], 54, v159
	v_cndmask_b32_e64 v84, v84, v204, s[42:43]
	v_cmp_gt_i32_e64 s[42:43], 55, v159
	v_cmp_gt_i32_e64 s[38:39], 53, v159
	s_and_b64 s[40:41], s[42:43], s[40:41]
	v_cmp_gt_i32_e64 s[36:37], 52, v159
	s_and_b64 s[38:39], s[40:41], s[38:39]
	v_cmp_gt_i32_e64 s[34:35], 51, v159
	s_and_b64 s[36:37], s[38:39], s[36:37]
	v_cmp_gt_i32_e64 s[30:31], 50, v159
	s_and_b64 s[34:35], s[36:37], s[34:35]
	v_cmp_gt_i32_e64 s[28:29], 49, v159
	s_and_b64 s[30:31], s[34:35], s[30:31]
	v_cmp_gt_i32_e64 s[26:27], 48, v159
	s_and_b64 s[28:29], s[30:31], s[28:29]
	v_cmp_gt_i32_e64 s[24:25], 39, v159
	s_and_b64 s[26:27], s[28:29], s[26:27]
	v_cmp_gt_i32_e64 s[22:23], 38, v159
	s_and_b64 s[24:25], s[26:27], s[24:25]
	v_cmp_gt_i32_e64 s[20:21], 37, v159
	s_and_b64 s[22:23], s[24:25], s[22:23]
	v_cmp_gt_i32_e64 s[18:19], 36, v159
	s_and_b64 s[20:21], s[22:23], s[20:21]
	v_cmp_gt_i32_e64 s[16:17], 35, v159
	s_and_b64 s[18:19], s[20:21], s[18:19]
	v_cmp_gt_i32_e64 s[14:15], 34, v159
	s_and_b64 s[16:17], s[18:19], s[16:17]
	v_cmp_gt_i32_e64 s[12:13], 33, v159
	s_and_b64 s[14:15], s[16:17], s[14:15]
	v_cmp_gt_i32_e32 vcc, 32, v159
	s_and_b64 s[12:13], s[14:15], s[12:13]
	s_and_b64 vcc, s[12:13], vcc
	v_cndmask_b32_e64 v99, v99, v204, s[72:73]
	v_cndmask_b32_e64 v98, v98, v204, s[70:71]
	v_cndmask_b32_e64 v97, v97, v204, s[68:69]
	v_cndmask_b32_e64 v96, v96, v204, s[66:67]
	v_cndmask_b32_e64 v95, v95, v204, s[64:65]
	v_cndmask_b32_e64 v94, v94, v204, s[62:63]
	v_cndmask_b32_e64 v93, v93, v204, s[60:61]
	v_cndmask_b32_e64 v92, v92, v204, s[58:59]
	v_cndmask_b32_e64 v91, v91, v204, s[56:57]
	v_cndmask_b32_e64 v90, v90, v204, s[54:55]
	v_cndmask_b32_e64 v89, v89, v204, s[52:53]
	v_cndmask_b32_e64 v88, v88, v204, s[50:51]
	v_cndmask_b32_e64 v87, v87, v204, s[48:49]
	v_cndmask_b32_e64 v86, v86, v204, s[46:47]
	v_cndmask_b32_e64 v85, v85, v204, s[44:45]
	v_cndmask_b32_e64 v83, v83, v204, s[42:43]
	v_cndmask_b32_e64 v82, v82, v204, s[40:41]
	v_cndmask_b32_e64 v81, v81, v204, s[38:39]
	v_cndmask_b32_e64 v80, v80, v204, s[36:37]
	v_cndmask_b32_e64 v79, v79, v204, s[34:35]
	v_cndmask_b32_e64 v78, v78, v204, s[30:31]
	v_cndmask_b32_e64 v77, v77, v204, s[28:29]
	v_cndmask_b32_e64 v76, v76, v204, s[26:27]
	v_cndmask_b32_e64 v75, v75, v204, s[24:25]
	v_cndmask_b32_e64 v74, v74, v204, s[22:23]
	v_cndmask_b32_e64 v73, v73, v204, s[20:21]
	v_cndmask_b32_e64 v72, v72, v204, s[18:19]
	v_cndmask_b32_e64 v71, v71, v204, s[16:17]
	v_cndmask_b32_e64 v70, v70, v204, s[14:15]
	v_cndmask_b32_e64 v69, v69, v204, s[12:13]
	v_cndmask_b32_e32 v68, v68, v204, vcc

.LBB0_929:
	s_add_i32 s4, s33, 0x8000
	s_and_b32 s4, s4, 0xc000
	s_add_i32 s12, s4, 0
	s_add_i32 s12, s12, 0x10000
	v_add_u32_e32 v76, s12, v152
	v_add_u32_e32 v77, v76, v153
	ds_read_b128 v[68:71], v77 offset:0
	ds_read_b128 v[72:75], v77 offset:0x2000
	v_add_u32_e32 v77, v76, v155
	ds_read_b128 v[116:119], v77 offset:0
	ds_read_b128 v[120:123], v77 offset:0x2000
	v_add_u32_e32 v77, v76, v156
	ds_read_b128 v[124:127], v77 offset:0
	ds_read_b128 v[128:131], v77 offset:0x2000
	v_add_u32_e32 v76, v76, v157
	ds_read_b128 v[132:135], v76 offset:0
	ds_read_b128 v[136:139], v76 offset:0x2000
	s_waitcnt lgkmcnt(4)
	s_add_i32 s3, s2, 0xbf
	s_cmp_le_i32 s3, s86
	v_mfma_f32_32x32x16_bf16 v[84:99], v[68:71], v[100:103], 0
	v_mfma_f32_32x32x16_bf16 v[84:99], v[116:119], v[104:107], v[84:99]
	v_mfma_f32_32x32x16_bf16 v[68:83], v[72:75], v[100:103], 0
	v_mfma_f32_32x32x16_bf16 v[68:83], v[120:123], v[104:107], v[68:83]
	s_waitcnt lgkmcnt(0)
	v_mfma_f32_32x32x16_bf16 v[84:99], v[124:127], v[108:111], v[84:99]
	v_mfma_f32_32x32x16_bf16 v[84:99], v[132:135], v[112:115], v[84:99]
	v_mfma_f32_32x32x16_bf16 v[68:83], v[128:131], v[108:111], v[68:83]
	v_mfma_f32_32x32x16_bf16 v[68:83], v[136:139], v[112:115], v[68:83]
	v_add_u32_e32 v162, s4, v158
	ds_read_b64_tr_b16 v[144:145], v162 offset:0
	ds_read_b64_tr_b16 v[146:147], v162 offset:0x800
	ds_read_b64_tr_b16 v[140:141], v162 offset:0x1000
	ds_read_b64_tr_b16 v[142:143], v162 offset:0x1800
	ds_read_b64_tr_b16 v[136:137], v162 offset:0x2000
	ds_read_b64_tr_b16 v[138:139], v162 offset:0x2800
	ds_read_b64_tr_b16 v[132:133], v162 offset:0x3000
	ds_read_b64_tr_b16 v[134:135], v162 offset:0x3800
	ds_read_b64_tr_b16 v[128:129], v162 offset:0x200
	ds_read_b64_tr_b16 v[130:131], v162 offset:0xa00
	ds_read_b64_tr_b16 v[124:125], v162 offset:0x1200
	ds_read_b64_tr_b16 v[126:127], v162 offset:0x1a00
	ds_read_b64_tr_b16 v[120:121], v162 offset:0x2200
	ds_read_b64_tr_b16 v[122:123], v162 offset:0x2a00
	ds_read_b64_tr_b16 v[116:117], v162 offset:0x3200
	ds_read_b64_tr_b16 v[118:119], v162 offset:0x3a00
	s_cbranch_scc1 .LBB0_931
	v_add_u32_e32 v163, 64, v159
	v_cmp_gt_i32_e64 s[70:71], 22, v163
	v_cmp_gt_i32_e64 s[72:73], 23, v163
	v_cmp_gt_i32_e64 s[68:69], 21, v163
	s_and_b64 s[70:71], s[72:73], s[70:71]
	v_cmp_gt_i32_e64 s[66:67], 20, v163
	s_and_b64 s[68:69], s[70:71], s[68:69]
	v_cmp_gt_i32_e64 s[64:65], 19, v163
	s_and_b64 s[66:67], s[68:69], s[66:67]
	v_cmp_gt_i32_e64 s[62:63], 18, v163
	s_and_b64 s[64:65], s[66:67], s[64:65]
	v_cmp_gt_i32_e64 s[60:61], 17, v163
	s_and_b64 s[62:63], s[64:65], s[62:63]
	v_cmp_gt_i32_e64 s[58:59], 16, v163
	s_and_b64 s[60:61], s[62:63], s[60:61]
	v_cmp_gt_i32_e64 s[56:57], 7, v163
	s_and_b64 s[58:59], s[60:61], s[58:59]
	v_cmp_gt_i32_e64 s[54:55], 6, v163
	s_and_b64 s[56:57], s[58:59], s[56:57]
	v_cmp_gt_i32_e64 s[52:53], 5, v163
	s_and_b64 s[54:55], s[56:57], s[54:55]
	v_cmp_gt_i32_e64 s[50:51], 4, v163
	s_and_b64 s[52:53], s[54:55], s[52:53]
	v_cmp_gt_i32_e64 s[48:49], 3, v163
	s_and_b64 s[50:51], s[52:53], s[50:51]
	v_cmp_gt_i32_e64 s[46:47], 2, v163
	s_and_b64 s[48:49], s[50:51], s[48:49]
	v_cmp_gt_i32_e64 s[44:45], 1, v163
	s_and_b64 s[46:47], s[48:49], s[46:47]
	v_cmp_gt_i32_e64 s[42:43], 0, v163
	s_and_b64 s[44:45], s[46:47], s[44:45]
	s_and_b64 s[42:43], s[44:45], s[42:43]
	v_cmp_gt_i32_e64 s[40:41], 54, v163
	v_cndmask_b32_e64 v84, v84, v204, s[42:43]
	v_cmp_gt_i32_e64 s[42:43], 55, v163
	v_cmp_gt_i32_e64 s[38:39], 53, v163
	s_and_b64 s[40:41], s[42:43], s[40:41]
	v_cmp_gt_i32_e64 s[36:37], 52, v163
	s_and_b64 s[38:39], s[40:41], s[38:39]
	v_cmp_gt_i32_e64 s[34:35], 51, v163
	s_and_b64 s[36:37], s[38:39], s[36:37]
	v_cmp_gt_i32_e64 s[30:31], 50, v163
	s_and_b64 s[34:35], s[36:37], s[34:35]
	v_cmp_gt_i32_e64 s[28:29], 49, v163
	s_and_b64 s[30:31], s[34:35], s[30:31]
	v_cmp_gt_i32_e64 s[26:27], 48, v163
	s_and_b64 s[28:29], s[30:31], s[28:29]
	v_cmp_gt_i32_e64 s[24:25], 39, v163
	s_and_b64 s[26:27], s[28:29], s[26:27]
	v_cmp_gt_i32_e64 s[22:23], 38, v163
	s_and_b64 s[24:25], s[26:27], s[24:25]
	v_cmp_gt_i32_e64 s[20:21], 37, v163
	s_and_b64 s[22:23], s[24:25], s[22:23]
	v_cmp_gt_i32_e64 s[18:19], 36, v163
	s_and_b64 s[20:21], s[22:23], s[20:21]
	v_cmp_gt_i32_e64 s[16:17], 35, v163
	s_and_b64 s[18:19], s[20:21], s[18:19]
	v_cmp_gt_i32_e64 s[14:15], 34, v163
	s_and_b64 s[16:17], s[18:19], s[16:17]
	v_cmp_gt_i32_e64 s[12:13], 33, v163
	s_and_b64 s[14:15], s[16:17], s[14:15]
	v_cmp_gt_i32_e32 vcc, 32, v163
	s_and_b64 s[12:13], s[14:15], s[12:13]
	s_and_b64 vcc, s[12:13], vcc
	v_cndmask_b32_e64 v99, v99, v204, s[72:73]
	v_cndmask_b32_e64 v98, v98, v204, s[70:71]
	v_cndmask_b32_e64 v97, v97, v204, s[68:69]
	v_cndmask_b32_e64 v96, v96, v204, s[66:67]
	v_cndmask_b32_e64 v95, v95, v204, s[64:65]
	v_cndmask_b32_e64 v94, v94, v204, s[62:63]
	v_cndmask_b32_e64 v93, v93, v204, s[60:61]
	v_cndmask_b32_e64 v92, v92, v204, s[58:59]
	v_cndmask_b32_e64 v91, v91, v204, s[56:57]
	v_cndmask_b32_e64 v90, v90, v204, s[54:55]
	v_cndmask_b32_e64 v89, v89, v204, s[52:53]
	v_cndmask_b32_e64 v88, v88, v204, s[50:51]
	v_cndmask_b32_e64 v87, v87, v204, s[48:49]
	v_cndmask_b32_e64 v86, v86, v204, s[46:47]
	v_cndmask_b32_e64 v85, v85, v204, s[44:45]
	v_cndmask_b32_e64 v83, v83, v204, s[42:43]
	v_cndmask_b32_e64 v82, v82, v204, s[40:41]
	v_cndmask_b32_e64 v81, v81, v204, s[38:39]
	v_cndmask_b32_e64 v80, v80, v204, s[36:37]
	v_cndmask_b32_e64 v79, v79, v204, s[34:35]
	v_cndmask_b32_e64 v78, v78, v204, s[30:31]
	v_cndmask_b32_e64 v77, v77, v204, s[28:29]
	v_cndmask_b32_e64 v76, v76, v204, s[26:27]
	v_cndmask_b32_e64 v75, v75, v204, s[24:25]
	v_cndmask_b32_e64 v74, v74, v204, s[22:23]
	v_cndmask_b32_e64 v73, v73, v204, s[20:21]
	v_cndmask_b32_e64 v72, v72, v204, s[18:19]
	v_cndmask_b32_e64 v71, v71, v204, s[16:17]
	v_cndmask_b32_e64 v70, v70, v204, s[14:15]
	v_cndmask_b32_e64 v69, v69, v204, s[12:13]
	v_cndmask_b32_e32 v68, v68, v204, vcc

.LBB0_947:
	s_add_i32 s4, s0, 0xc000
	s_and_b32 s4, s4, 0xc000
	s_add_i32 s12, s4, 0
	s_add_i32 s12, s12, 0x10000
	v_add_u32_e32 v76, s12, v154
	v_add_u32_e32 v77, v76, v156
	ds_read_b128 v[68:71], v77 offset:0
	ds_read_b128 v[72:75], v77 offset:0x2000
	v_add_u32_e32 v77, v76, v157
	ds_read_b128 v[116:119], v77 offset:0
	ds_read_b128 v[120:123], v77 offset:0x2000
	v_add_u32_e32 v77, v76, v158
	ds_read_b128 v[124:127], v77 offset:0
	ds_read_b128 v[128:131], v77 offset:0x2000
	v_add_u32_e32 v76, v76, v159
	ds_read_b128 v[132:135], v76 offset:0
	ds_read_b128 v[136:139], v76 offset:0x2000
	s_waitcnt lgkmcnt(4)
	s_add_i32 s3, s2, 0xff
	s_cmp_le_u32 s3, s79
	v_mfma_f32_32x32x16_bf16 v[84:99], v[68:71], v[100:103], 0
	v_mfma_f32_32x32x16_bf16 v[84:99], v[116:119], v[104:107], v[84:99]
	v_mfma_f32_32x32x16_bf16 v[68:83], v[72:75], v[100:103], 0
	v_mfma_f32_32x32x16_bf16 v[68:83], v[120:123], v[104:107], v[68:83]
	s_waitcnt lgkmcnt(0)
	v_mfma_f32_32x32x16_bf16 v[84:99], v[124:127], v[108:111], v[84:99]
	v_mfma_f32_32x32x16_bf16 v[84:99], v[132:135], v[112:115], v[84:99]
	v_mfma_f32_32x32x16_bf16 v[68:83], v[128:131], v[108:111], v[68:83]
	v_mfma_f32_32x32x16_bf16 v[68:83], v[136:139], v[112:115], v[68:83]
	v_add_u32_e32 v164, s4, v160
	ds_read_b64_tr_b16 v[144:145], v164 offset:0
	ds_read_b64_tr_b16 v[146:147], v164 offset:0x800
	ds_read_b64_tr_b16 v[140:141], v164 offset:0x1000
	ds_read_b64_tr_b16 v[142:143], v164 offset:0x1800
	ds_read_b64_tr_b16 v[136:137], v164 offset:0x2000
	ds_read_b64_tr_b16 v[138:139], v164 offset:0x2800
	ds_read_b64_tr_b16 v[132:133], v164 offset:0x3000
	ds_read_b64_tr_b16 v[134:135], v164 offset:0x3800
	ds_read_b64_tr_b16 v[128:129], v164 offset:0x200
	ds_read_b64_tr_b16 v[130:131], v164 offset:0xa00
	ds_read_b64_tr_b16 v[124:125], v164 offset:0x1200
	ds_read_b64_tr_b16 v[126:127], v164 offset:0x1a00
	ds_read_b64_tr_b16 v[120:121], v164 offset:0x2200
	ds_read_b64_tr_b16 v[122:123], v164 offset:0x2a00
	ds_read_b64_tr_b16 v[116:117], v164 offset:0x3200
	ds_read_b64_tr_b16 v[118:119], v164 offset:0x3a00
	s_cbranch_scc1 .LBB0_949
	v_cmp_gt_i32_e64 s[70:71], 22, v161
	v_cmp_gt_i32_e64 s[72:73], 23, v161
	v_cmp_gt_i32_e64 s[68:69], 21, v161
	s_and_b64 s[70:71], s[72:73], s[70:71]
	v_cmp_gt_i32_e64 s[66:67], 20, v161
	s_and_b64 s[68:69], s[70:71], s[68:69]
	v_cmp_gt_i32_e64 s[64:65], 19, v161
	s_and_b64 s[66:67], s[68:69], s[66:67]
	v_cmp_gt_i32_e64 s[62:63], 18, v161
	s_and_b64 s[64:65], s[66:67], s[64:65]
	v_cmp_gt_i32_e64 s[60:61], 17, v161
	s_and_b64 s[62:63], s[64:65], s[62:63]
	v_cmp_gt_i32_e64 s[58:59], 16, v161
	s_and_b64 s[60:61], s[62:63], s[60:61]
	v_cmp_gt_i32_e64 s[56:57], 7, v161
	s_and_b64 s[58:59], s[60:61], s[58:59]
	v_cmp_gt_i32_e64 s[54:55], 6, v161
	s_and_b64 s[56:57], s[58:59], s[56:57]
	v_cmp_gt_i32_e64 s[52:53], 5, v161
	s_and_b64 s[54:55], s[56:57], s[54:55]
	v_cmp_gt_i32_e64 s[50:51], 4, v161
	s_and_b64 s[52:53], s[54:55], s[52:53]
	v_cmp_gt_i32_e64 s[48:49], 3, v161
	s_and_b64 s[50:51], s[52:53], s[50:51]
	v_cmp_gt_i32_e64 s[46:47], 2, v161
	s_and_b64 s[48:49], s[50:51], s[48:49]
	v_cmp_gt_i32_e64 s[44:45], 1, v161
	s_and_b64 s[46:47], s[48:49], s[46:47]
	v_cmp_gt_i32_e64 s[42:43], 0, v161
	s_and_b64 s[44:45], s[46:47], s[44:45]
	s_and_b64 s[42:43], s[44:45], s[42:43]
	v_cmp_gt_i32_e64 s[40:41], 54, v161
	v_cndmask_b32_e64 v84, v84, v204, s[42:43]
	v_cmp_gt_i32_e64 s[42:43], 55, v161
	v_cmp_gt_i32_e64 s[38:39], 53, v161
	s_and_b64 s[40:41], s[42:43], s[40:41]
	v_cmp_gt_i32_e64 s[36:37], 52, v161
	s_and_b64 s[38:39], s[40:41], s[38:39]
	v_cmp_gt_i32_e64 s[34:35], 51, v161
	s_and_b64 s[36:37], s[38:39], s[36:37]
	v_cmp_gt_i32_e64 s[30:31], 50, v161
	s_and_b64 s[34:35], s[36:37], s[34:35]
	v_cmp_gt_i32_e64 s[28:29], 49, v161
	s_and_b64 s[30:31], s[34:35], s[30:31]
	v_cmp_gt_i32_e64 s[26:27], 48, v161
	s_and_b64 s[28:29], s[30:31], s[28:29]
	v_cmp_gt_i32_e64 s[24:25], 39, v161
	s_and_b64 s[26:27], s[28:29], s[26:27]
	v_cmp_gt_i32_e64 s[22:23], 38, v161
	s_and_b64 s[24:25], s[26:27], s[24:25]
	v_cmp_gt_i32_e64 s[20:21], 37, v161
	s_and_b64 s[22:23], s[24:25], s[22:23]
	v_cmp_gt_i32_e64 s[18:19], 36, v161
	s_and_b64 s[20:21], s[22:23], s[20:21]
	v_cmp_gt_i32_e64 s[16:17], 35, v161
	s_and_b64 s[18:19], s[20:21], s[18:19]
	v_cmp_gt_i32_e64 s[14:15], 34, v161
	s_and_b64 s[16:17], s[18:19], s[16:17]
	v_cmp_gt_i32_e64 s[12:13], 33, v161
	s_and_b64 s[14:15], s[16:17], s[14:15]
	v_cmp_gt_i32_e32 vcc, 32, v161
	s_and_b64 s[12:13], s[14:15], s[12:13]
	s_and_b64 vcc, s[12:13], vcc
	v_cndmask_b32_e64 v99, v99, v204, s[72:73]
	v_cndmask_b32_e64 v98, v98, v204, s[70:71]
	v_cndmask_b32_e64 v97, v97, v204, s[68:69]
	v_cndmask_b32_e64 v96, v96, v204, s[66:67]
	v_cndmask_b32_e64 v95, v95, v204, s[64:65]
	v_cndmask_b32_e64 v94, v94, v204, s[62:63]
	v_cndmask_b32_e64 v93, v93, v204, s[60:61]
	v_cndmask_b32_e64 v92, v92, v204, s[58:59]
	v_cndmask_b32_e64 v91, v91, v204, s[56:57]
	v_cndmask_b32_e64 v90, v90, v204, s[54:55]
	v_cndmask_b32_e64 v89, v89, v204, s[52:53]
	v_cndmask_b32_e64 v88, v88, v204, s[50:51]
	v_cndmask_b32_e64 v87, v87, v204, s[48:49]
	v_cndmask_b32_e64 v86, v86, v204, s[46:47]
	v_cndmask_b32_e64 v85, v85, v204, s[44:45]
	v_cndmask_b32_e64 v83, v83, v204, s[42:43]
	v_cndmask_b32_e64 v82, v82, v204, s[40:41]
	v_cndmask_b32_e64 v81, v81, v204, s[38:39]
	v_cndmask_b32_e64 v80, v80, v204, s[36:37]
	v_cndmask_b32_e64 v79, v79, v204, s[34:35]
	v_cndmask_b32_e64 v78, v78, v204, s[30:31]
	v_cndmask_b32_e64 v77, v77, v204, s[28:29]
	v_cndmask_b32_e64 v76, v76, v204, s[26:27]
	v_cndmask_b32_e64 v75, v75, v204, s[24:25]
	v_cndmask_b32_e64 v74, v74, v204, s[22:23]
	v_cndmask_b32_e64 v73, v73, v204, s[20:21]
	v_cndmask_b32_e64 v72, v72, v204, s[18:19]
	v_cndmask_b32_e64 v71, v71, v204, s[16:17]
	v_cndmask_b32_e64 v70, v70, v204, s[14:15]
	v_cndmask_b32_e64 v69, v69, v204, s[12:13]
	v_cndmask_b32_e32 v68, v68, v204, vcc

.LBB0_955:
	s_add_i32 s4, s0, 0x8000
	s_and_b32 s4, s4, 0xc000
	s_add_i32 s12, s4, 0
	s_add_i32 s12, s12, 0x10000
	v_add_u32_e32 v76, s12, v154
	v_add_u32_e32 v77, v76, v156
	ds_read_b128 v[68:71], v77 offset:0
	ds_read_b128 v[72:75], v77 offset:0x2000
	v_add_u32_e32 v77, v76, v157
	ds_read_b128 v[116:119], v77 offset:0
	ds_read_b128 v[120:123], v77 offset:0x2000
	v_add_u32_e32 v77, v76, v158
	ds_read_b128 v[124:127], v77 offset:0
	ds_read_b128 v[128:131], v77 offset:0x2000
	v_add_u32_e32 v76, v76, v159
	ds_read_b128 v[132:135], v76 offset:0
	ds_read_b128 v[136:139], v76 offset:0x2000
	s_waitcnt lgkmcnt(4)
	s_add_i32 s3, s2, 0xbf
	s_cmp_le_i32 s3, s79
	v_mfma_f32_32x32x16_bf16 v[84:99], v[68:71], v[100:103], 0
	v_mfma_f32_32x32x16_bf16 v[84:99], v[116:119], v[104:107], v[84:99]
	v_mfma_f32_32x32x16_bf16 v[68:83], v[72:75], v[100:103], 0
	v_mfma_f32_32x32x16_bf16 v[68:83], v[120:123], v[104:107], v[68:83]
	s_waitcnt lgkmcnt(0)
	v_mfma_f32_32x32x16_bf16 v[84:99], v[124:127], v[108:111], v[84:99]
	v_mfma_f32_32x32x16_bf16 v[84:99], v[132:135], v[112:115], v[84:99]
	v_mfma_f32_32x32x16_bf16 v[68:83], v[128:131], v[108:111], v[68:83]
	v_mfma_f32_32x32x16_bf16 v[68:83], v[136:139], v[112:115], v[68:83]
	v_add_u32_e32 v164, s4, v160
	ds_read_b64_tr_b16 v[144:145], v164 offset:0
	ds_read_b64_tr_b16 v[146:147], v164 offset:0x800
	ds_read_b64_tr_b16 v[140:141], v164 offset:0x1000
	ds_read_b64_tr_b16 v[142:143], v164 offset:0x1800
	ds_read_b64_tr_b16 v[136:137], v164 offset:0x2000
	ds_read_b64_tr_b16 v[138:139], v164 offset:0x2800
	ds_read_b64_tr_b16 v[132:133], v164 offset:0x3000
	ds_read_b64_tr_b16 v[134:135], v164 offset:0x3800
	ds_read_b64_tr_b16 v[128:129], v164 offset:0x200
	ds_read_b64_tr_b16 v[130:131], v164 offset:0xa00
	ds_read_b64_tr_b16 v[124:125], v164 offset:0x1200
	ds_read_b64_tr_b16 v[126:127], v164 offset:0x1a00
	ds_read_b64_tr_b16 v[120:121], v164 offset:0x2200
	ds_read_b64_tr_b16 v[122:123], v164 offset:0x2a00
	ds_read_b64_tr_b16 v[116:117], v164 offset:0x3200
	ds_read_b64_tr_b16 v[118:119], v164 offset:0x3a00
	s_cbranch_scc1 .LBB0_957
	v_add_u32_e32 v165, 64, v161
	v_cmp_gt_i32_e64 s[70:71], 22, v165
	v_cmp_gt_i32_e64 s[72:73], 23, v165
	v_cmp_gt_i32_e64 s[68:69], 21, v165
	s_and_b64 s[70:71], s[72:73], s[70:71]
	v_cmp_gt_i32_e64 s[66:67], 20, v165
	s_and_b64 s[68:69], s[70:71], s[68:69]
	v_cmp_gt_i32_e64 s[64:65], 19, v165
	s_and_b64 s[66:67], s[68:69], s[66:67]
	v_cmp_gt_i32_e64 s[62:63], 18, v165
	s_and_b64 s[64:65], s[66:67], s[64:65]
	v_cmp_gt_i32_e64 s[60:61], 17, v165
	s_and_b64 s[62:63], s[64:65], s[62:63]
	v_cmp_gt_i32_e64 s[58:59], 16, v165
	s_and_b64 s[60:61], s[62:63], s[60:61]
	v_cmp_gt_i32_e64 s[56:57], 7, v165
	s_and_b64 s[58:59], s[60:61], s[58:59]
	v_cmp_gt_i32_e64 s[54:55], 6, v165
	s_and_b64 s[56:57], s[58:59], s[56:57]
	v_cmp_gt_i32_e64 s[52:53], 5, v165
	s_and_b64 s[54:55], s[56:57], s[54:55]
	v_cmp_gt_i32_e64 s[50:51], 4, v165
	s_and_b64 s[52:53], s[54:55], s[52:53]
	v_cmp_gt_i32_e64 s[48:49], 3, v165
	s_and_b64 s[50:51], s[52:53], s[50:51]
	v_cmp_gt_i32_e64 s[46:47], 2, v165
	s_and_b64 s[48:49], s[50:51], s[48:49]
	v_cmp_gt_i32_e64 s[44:45], 1, v165
	s_and_b64 s[46:47], s[48:49], s[46:47]
	v_cmp_gt_i32_e64 s[42:43], 0, v165
	s_and_b64 s[44:45], s[46:47], s[44:45]
	s_and_b64 s[42:43], s[44:45], s[42:43]
	v_cmp_gt_i32_e64 s[40:41], 54, v165
	v_cndmask_b32_e64 v84, v84, v204, s[42:43]
	v_cmp_gt_i32_e64 s[42:43], 55, v165
	v_cmp_gt_i32_e64 s[38:39], 53, v165
	s_and_b64 s[40:41], s[42:43], s[40:41]
	v_cmp_gt_i32_e64 s[36:37], 52, v165
	s_and_b64 s[38:39], s[40:41], s[38:39]
	v_cmp_gt_i32_e64 s[34:35], 51, v165
	s_and_b64 s[36:37], s[38:39], s[36:37]
	v_cmp_gt_i32_e64 s[30:31], 50, v165
	s_and_b64 s[34:35], s[36:37], s[34:35]
	v_cmp_gt_i32_e64 s[28:29], 49, v165
	s_and_b64 s[30:31], s[34:35], s[30:31]
	v_cmp_gt_i32_e64 s[26:27], 48, v165
	s_and_b64 s[28:29], s[30:31], s[28:29]
	v_cmp_gt_i32_e64 s[24:25], 39, v165
	s_and_b64 s[26:27], s[28:29], s[26:27]
	v_cmp_gt_i32_e64 s[22:23], 38, v165
	s_and_b64 s[24:25], s[26:27], s[24:25]
	v_cmp_gt_i32_e64 s[20:21], 37, v165
	s_and_b64 s[22:23], s[24:25], s[22:23]
	v_cmp_gt_i32_e64 s[18:19], 36, v165
	s_and_b64 s[20:21], s[22:23], s[20:21]
	v_cmp_gt_i32_e64 s[16:17], 35, v165
	s_and_b64 s[18:19], s[20:21], s[18:19]
	v_cmp_gt_i32_e64 s[14:15], 34, v165
	s_and_b64 s[16:17], s[18:19], s[16:17]
	v_cmp_gt_i32_e64 s[12:13], 33, v165
	s_and_b64 s[14:15], s[16:17], s[14:15]
	v_cmp_gt_i32_e32 vcc, 32, v165
	s_and_b64 s[12:13], s[14:15], s[12:13]
	s_and_b64 vcc, s[12:13], vcc
	v_cndmask_b32_e64 v99, v99, v204, s[72:73]
	v_cndmask_b32_e64 v98, v98, v204, s[70:71]
	v_cndmask_b32_e64 v97, v97, v204, s[68:69]
	v_cndmask_b32_e64 v96, v96, v204, s[66:67]
	v_cndmask_b32_e64 v95, v95, v204, s[64:65]
	v_cndmask_b32_e64 v94, v94, v204, s[62:63]
	v_cndmask_b32_e64 v93, v93, v204, s[60:61]
	v_cndmask_b32_e64 v92, v92, v204, s[58:59]
	v_cndmask_b32_e64 v91, v91, v204, s[56:57]
	v_cndmask_b32_e64 v90, v90, v204, s[54:55]
	v_cndmask_b32_e64 v89, v89, v204, s[52:53]
	v_cndmask_b32_e64 v88, v88, v204, s[50:51]
	v_cndmask_b32_e64 v87, v87, v204, s[48:49]
	v_cndmask_b32_e64 v86, v86, v204, s[46:47]
	v_cndmask_b32_e64 v85, v85, v204, s[44:45]
	v_cndmask_b32_e64 v83, v83, v204, s[42:43]
	v_cndmask_b32_e64 v82, v82, v204, s[40:41]
	v_cndmask_b32_e64 v81, v81, v204, s[38:39]
	v_cndmask_b32_e64 v80, v80, v204, s[36:37]
	v_cndmask_b32_e64 v79, v79, v204, s[34:35]
	v_cndmask_b32_e64 v78, v78, v204, s[30:31]
	v_cndmask_b32_e64 v77, v77, v204, s[28:29]
	v_cndmask_b32_e64 v76, v76, v204, s[26:27]
	v_cndmask_b32_e64 v75, v75, v204, s[24:25]
	v_cndmask_b32_e64 v74, v74, v204, s[22:23]
	v_cndmask_b32_e64 v73, v73, v204, s[20:21]
	v_cndmask_b32_e64 v72, v72, v204, s[18:19]
	v_cndmask_b32_e64 v71, v71, v204, s[16:17]
	v_cndmask_b32_e64 v70, v70, v204, s[14:15]
	v_cndmask_b32_e64 v69, v69, v204, s[12:13]
	v_cndmask_b32_e32 v68, v68, v204, vcc

.LBB0_971:
	s_add_i32 s0, s6, 0xc0
	s_cmp_lt_i32 s0, s88
	s_cselect_b64 s[0:1], -1, 0
	s_xor_b64 s[2:3], s[96:97], -1
	s_and_b64 s[0:1], s[0:1], s[2:3]
	s_and_saveexec_b64 s[2:3], s[0:1]
	s_cbranch_execz .LBB0_977
	s_add_i32 s1, s94, 0xc000
	s_and_b32 s1, s1, 0xc000
	s_add_i32 s4, s1, 0
	s_add_i32 s4, s4, 0x10000
	v_add_u32_e32 v2, s4, v206
	v_add_u32_e32 v76, v2, v207
	ds_read_b128 v[68:71], v76 offset:0
	ds_read_b128 v[72:75], v76 offset:0x2000
	v_add_u32_e32 v76, v2, v208
	ds_read_b128 v[132:135], v76 offset:0
	ds_read_b128 v[136:139], v76 offset:0x2000
	v_add_u32_e32 v76, v2, v209
	ds_read_b128 v[140:143], v76 offset:0
	ds_read_b128 v[144:147], v76 offset:0x2000
	v_add_u32_e32 v76, v2, v210
	ds_read_b128 v[148:151], v76 offset:0
	ds_read_b128 v[152:155], v76 offset:0x2000
	s_waitcnt lgkmcnt(4)
	s_add_i32 s0, s6, 0xff
	s_cmp_lt_u32 s0, s78
	v_mfma_f32_32x32x16_bf16 v[84:99], v[68:71], v[124:127], 0
	v_mfma_f32_32x32x16_bf16 v[84:99], v[132:135], v[100:103], v[84:99]
	v_mfma_f32_32x32x16_bf16 v[68:83], v[72:75], v[124:127], 0
	v_mfma_f32_32x32x16_bf16 v[68:83], v[136:139], v[100:103], v[68:83]
	s_waitcnt lgkmcnt(0)
	v_mfma_f32_32x32x16_bf16 v[84:99], v[140:143], v[104:107], v[84:99]
	v_add_u32_e32 v140, v2, v212
	ds_read_b128 v[132:135], v140 offset:0
	ds_read_b128 v[136:139], v140 offset:0x2000
	v_add_u32_e32 v156, v2, v214
	v_mfma_f32_32x32x16_bf16 v[68:83], v[144:147], v[104:107], v[68:83]
	v_mfma_f32_32x32x16_bf16 v[84:99], v[148:151], v[108:111], v[84:99]
	v_add_u32_e32 v148, v2, v213
	ds_read_b128 v[140:143], v148 offset:0
	ds_read_b128 v[144:147], v148 offset:0x2000
	ds_read_b128 v[148:151], v156 offset:0
	v_add_u32_e32 v2, v2, v215
	v_mfma_f32_32x32x16_bf16 v[68:83], v[152:155], v[108:111], v[68:83]
	ds_read_b128 v[152:155], v156 offset:0x2000
	ds_read_b128 v[156:159], v2 offset:0
	ds_read_b128 v[160:163], v2 offset:0x2000
	s_waitcnt lgkmcnt(4)
	v_mfma_f32_32x32x16_bf16 v[84:99], v[132:135], v[112:115], v[84:99]
	v_mfma_f32_32x32x16_bf16 v[84:99], v[140:143], v[116:119], v[84:99]
	v_mfma_f32_32x32x16_bf16 v[68:83], v[136:139], v[112:115], v[68:83]
	v_mfma_f32_32x32x16_bf16 v[68:83], v[144:147], v[116:119], v[68:83]
	s_waitcnt lgkmcnt(0)
	v_mfma_f32_32x32x16_bf16 v[84:99], v[148:151], v[120:123], v[84:99]
	v_mfma_f32_32x32x16_bf16 v[84:99], v[156:159], v[128:131], v[84:99]
	v_mfma_f32_32x32x16_bf16 v[68:83], v[152:155], v[120:123], v[68:83]
	v_mfma_f32_32x32x16_bf16 v[68:83], v[160:163], v[128:131], v[68:83]
	v_add_u32_e32 v2, s1, v216
	ds_read_b64_tr_b16 v[160:161], v2 offset:0
	ds_read_b64_tr_b16 v[162:163], v2 offset:0x800
	ds_read_b64_tr_b16 v[156:157], v2 offset:0x1000
	ds_read_b64_tr_b16 v[158:159], v2 offset:0x1800
	ds_read_b64_tr_b16 v[152:153], v2 offset:0x2000
	ds_read_b64_tr_b16 v[154:155], v2 offset:0x2800
	ds_read_b64_tr_b16 v[148:149], v2 offset:0x3000
	ds_read_b64_tr_b16 v[150:151], v2 offset:0x3800
	ds_read_b64_tr_b16 v[144:145], v2 offset:0x200
	ds_read_b64_tr_b16 v[146:147], v2 offset:0xa00
	ds_read_b64_tr_b16 v[140:141], v2 offset:0x1200
	ds_read_b64_tr_b16 v[142:143], v2 offset:0x1a00
	ds_read_b64_tr_b16 v[136:137], v2 offset:0x2200
	ds_read_b64_tr_b16 v[138:139], v2 offset:0x2a00
	ds_read_b64_tr_b16 v[132:133], v2 offset:0x3200
	ds_read_b64_tr_b16 v[134:135], v2 offset:0x3a00
	s_nop 10
	v_max_f32_e64 v77, -v77, -v77
	v_min_f32_e32 v77, 0x42a00000, v77
	v_max_f32_e64 v82, -v82, -v82
	v_exp_f32_e32 v195, v77
	v_max_f32_e64 v77, -v94, -v94
	v_max_f32_e64 v78, -v78, -v78
	v_min_f32_e32 v82, 0x42a00000, v82
	v_min_f32_e32 v77, 0x42a00000, v77
	v_min_f32_e32 v78, 0x42a00000, v78
	v_exp_f32_e32 v228, v82
	v_max_f32_e64 v82, -v99, -v99
	v_exp_f32_e32 v196, v77
	v_exp_f32_e32 v198, v78
	v_max_f32_e64 v78, -v95, -v95
	v_max_f32_e64 v79, -v79, -v79
	v_min_f32_e32 v82, 0x42a00000, v82
	v_min_f32_e32 v78, 0x42a00000, v78
	v_min_f32_e32 v79, 0x42a00000, v79
	v_exp_f32_e32 v227, v82
	v_exp_f32_e32 v197, v78
	v_exp_f32_e32 v199, v79
	v_max_f32_e64 v79, -v96, -v96
	v_max_f32_e64 v80, -v80, -v80
	v_max_f32_e64 v84, -v84, -v84
	v_max_f32_e64 v69, -v69, -v69
	v_max_f32_e64 v70, -v70, -v70
	v_max_f32_e64 v71, -v71, -v71
	v_max_f32_e64 v72, -v72, -v72
	v_max_f32_e64 v73, -v73, -v73
	v_max_f32_e64 v74, -v74, -v74
	v_max_f32_e64 v75, -v75, -v75
	v_max_f32_e64 v76, -v76, -v76
	v_min_f32_e32 v79, 0x42a00000, v79
	v_min_f32_e32 v80, 0x42a00000, v80
	v_min_f32_e32 v84, 0x42a00000, v84
	v_min_f32_e32 v69, 0x42a00000, v69
	v_min_f32_e32 v70, 0x42a00000, v70
	v_min_f32_e32 v71, 0x42a00000, v71
	v_min_f32_e32 v72, 0x42a00000, v72
	v_min_f32_e32 v73, 0x42a00000, v73
	v_min_f32_e32 v74, 0x42a00000, v74
	v_min_f32_e32 v75, 0x42a00000, v75
	v_min_f32_e32 v76, 0x42a00000, v76
	v_add_f32_e32 v94, 1.0, v196
	v_exp_f32_e32 v222, v79
	v_exp_f32_e32 v224, v80
	v_max_f32_e64 v80, -v97, -v97
	v_max_f32_e64 v81, -v81, -v81
	v_add_f32_e32 v82, 1.0, v228
	v_exp_f32_e32 v170, v84
	v_max_f32_e64 v84, -v85, -v85
	v_exp_f32_e32 v185, v69
	v_max_f32_e64 v69, -v86, -v86
	v_exp_f32_e32 v186, v70
	v_max_f32_e64 v70, -v87, -v87
	v_exp_f32_e32 v187, v71
	v_max_f32_e64 v71, -v88, -v88
	v_exp_f32_e32 v188, v72
	v_max_f32_e64 v72, -v89, -v89
	v_exp_f32_e32 v189, v73
	v_max_f32_e64 v73, -v90, -v90
	v_exp_f32_e32 v190, v74
	v_max_f32_e64 v74, -v91, -v91
	v_exp_f32_e32 v191, v75
	v_max_f32_e64 v75, -v92, -v92
	v_exp_f32_e32 v194, v76
	v_max_f32_e64 v76, -v93, -v93
	v_rcp_f32_e32 v78, v94
	v_add_f32_e32 v94, 1.0, v198
	v_min_f32_e32 v80, 0x42a00000, v80
	v_min_f32_e32 v81, 0x42a00000, v81
	v_rcp_f32_e32 v182, v82
	v_add_f32_e32 v82, 1.0, v227
	v_max_f32_e64 v68, -v68, -v68
	v_min_f32_e32 v84, 0x42a00000, v84
	v_min_f32_e32 v69, 0x42a00000, v69
	v_min_f32_e32 v70, 0x42a00000, v70
	v_min_f32_e32 v71, 0x42a00000, v71
	v_min_f32_e32 v72, 0x42a00000, v72
	v_min_f32_e32 v73, 0x42a00000, v73
	v_min_f32_e32 v74, 0x42a00000, v74
	v_min_f32_e32 v75, 0x42a00000, v75
	v_min_f32_e32 v76, 0x42a00000, v76
	v_rcp_f32_e32 v168, v94
	v_add_f32_e32 v94, 1.0, v197
	v_exp_f32_e32 v223, v80
	v_exp_f32_e32 v225, v81
	v_max_f32_e64 v81, -v98, -v98
	v_rcp_f32_e32 v173, v82
	v_max_f32_e64 v82, -v83, -v83
	v_min_f32_e32 v68, 0x42a00000, v68
	v_exp_f32_e32 v171, v84
	v_exp_f32_e32 v174, v69
	v_exp_f32_e32 v175, v70
	v_exp_f32_e32 v178, v71
	v_exp_f32_e32 v179, v72
	v_exp_f32_e32 v180, v73
	v_exp_f32_e32 v181, v74
	v_exp_f32_e32 v192, v75
	v_exp_f32_e32 v193, v76
	v_rcp_f32_e32 v79, v94
	v_add_f32_e32 v94, 1.0, v199
	v_min_f32_e32 v81, 0x42a00000, v81
	v_min_f32_e32 v82, 0x42a00000, v82
	v_exp_f32_e32 v184, v68
	v_rcp_f32_e32 v169, v94
	v_add_f32_e32 v94, 1.0, v222
	v_exp_f32_e32 v226, v81
	v_exp_f32_e32 v229, v82
	v_rcp_f32_e32 v80, v94
	v_add_f32_e32 v94, 1.0, v224
	v_rcp_f32_e32 v176, v94
	v_add_f32_e32 v94, 1.0, v223
	v_add_f32_e32 v85, 1.0, v171
	v_add_f32_e32 v86, 1.0, v174
	v_add_f32_e32 v87, 1.0, v175
	v_add_f32_e32 v88, 1.0, v178
	v_add_f32_e32 v89, 1.0, v179
	v_add_f32_e32 v90, 1.0, v180
	v_add_f32_e32 v91, 1.0, v181
	v_add_f32_e32 v92, 1.0, v192
	v_add_f32_e32 v93, 1.0, v193
	v_rcp_f32_e32 v81, v94
	v_add_f32_e32 v94, 1.0, v225
	v_add_f32_e32 v68, 1.0, v170
	v_add_f32_e32 v84, 1.0, v184
	v_rcp_f32_e32 v69, v85
	v_add_f32_e32 v85, 1.0, v185
	v_rcp_f32_e32 v70, v86
	v_add_f32_e32 v86, 1.0, v186
	v_rcp_f32_e32 v71, v87
	v_add_f32_e32 v87, 1.0, v187
	v_rcp_f32_e32 v72, v88
	v_add_f32_e32 v88, 1.0, v188
	v_rcp_f32_e32 v73, v89
	v_add_f32_e32 v89, 1.0, v189
	v_rcp_f32_e32 v74, v90
	v_add_f32_e32 v90, 1.0, v190
	v_rcp_f32_e32 v75, v91
	v_add_f32_e32 v91, 1.0, v191
	v_rcp_f32_e32 v76, v92
	v_add_f32_e32 v92, 1.0, v194
	v_rcp_f32_e32 v77, v93
	v_add_f32_e32 v93, 1.0, v195
	v_rcp_f32_e32 v177, v94
	v_add_f32_e32 v94, 1.0, v226
	v_add_f32_e32 v183, 1.0, v229
	v_rcp_f32_e32 v68, v68
	v_rcp_f32_e32 v84, v84
	v_rcp_f32_e32 v85, v85
	v_rcp_f32_e32 v86, v86
	v_rcp_f32_e32 v87, v87
	v_rcp_f32_e32 v88, v88
	v_rcp_f32_e32 v89, v89
	v_rcp_f32_e32 v90, v90
	v_rcp_f32_e32 v91, v91
	v_rcp_f32_e32 v92, v92
	v_rcp_f32_e32 v93, v93
	v_rcp_f32_e32 v172, v94
	v_rcp_f32_e32 v183, v183
	v_pk_mul_f32 v[94:95], v[170:171], v[68:69]
	v_pk_mul_f32 v[96:97], v[174:175], v[70:71]
	v_pk_mul_f32 v[98:99], v[178:179], v[72:73]
	v_pk_mul_f32 v[170:171], v[180:181], v[74:75]
	v_pk_mul_f32 v[174:175], v[192:193], v[76:77]
	v_pk_mul_f32 v[82:83], v[196:197], v[78:79]
	v_pk_mul_f32 v[178:179], v[222:223], v[80:81]
	v_pk_mul_f32 v[180:181], v[226:227], v[172:173]
	v_pk_mul_f32 v[184:185], v[184:185], v[84:85]
	v_pk_mul_f32 v[186:187], v[186:187], v[86:87]
	v_pk_mul_f32 v[188:189], v[188:189], v[88:89]
	v_pk_mul_f32 v[190:191], v[190:191], v[90:91]
	v_pk_mul_f32 v[192:193], v[194:195], v[92:93]
	v_pk_mul_f32 v[194:195], v[198:199], v[168:169]
	v_pk_mul_f32 v[196:197], v[224:225], v[176:177]
	v_pk_mul_f32 v[198:199], v[228:229], v[182:183]
	s_cbranch_scc1 .LBB0_974
	v_cmp_lt_i32_e64 s[72:73], 26, v217
	v_cmp_lt_i32_e64 s[74:75], 27, v217
	v_cmp_lt_i32_e64 s[70:71], 25, v217
	s_or_b64 s[72:73], s[74:75], s[72:73]
	v_cmp_lt_i32_e64 s[68:69], 24, v217
	s_or_b64 s[70:71], s[72:73], s[70:71]
	v_cmp_lt_i32_e64 s[66:67], 19, v217
	s_or_b64 s[68:69], s[70:71], s[68:69]
	v_cmp_lt_i32_e64 s[64:65], 18, v217
	s_or_b64 s[66:67], s[68:69], s[66:67]
	v_cmp_lt_i32_e64 s[62:63], 17, v217
	s_or_b64 s[64:65], s[66:67], s[64:65]
	v_cmp_lt_i32_e64 s[60:61], 16, v217
	s_or_b64 s[62:63], s[64:65], s[62:63]
	v_cmp_lt_i32_e64 s[58:59], 11, v217
	s_or_b64 s[60:61], s[62:63], s[60:61]
	v_cmp_lt_i32_e64 s[56:57], 10, v217
	s_or_b64 s[58:59], s[60:61], s[58:59]
	v_cmp_lt_i32_e64 s[54:55], 9, v217
	s_or_b64 s[56:57], s[58:59], s[56:57]
	v_cmp_lt_i32_e64 s[52:53], 8, v217
	s_or_b64 s[54:55], s[56:57], s[54:55]
	v_cmp_lt_i32_e64 s[50:51], 3, v217
	s_or_b64 s[52:53], s[54:55], s[52:53]
	v_cmp_lt_i32_e64 s[48:49], 2, v217
	s_or_b64 s[50:51], s[52:53], s[50:51]
	v_cmp_lt_i32_e64 s[46:47], 1, v217
	s_or_b64 s[48:49], s[50:51], s[48:49]
	v_cmp_lt_i32_e64 s[44:45], 0, v217
	s_or_b64 s[46:47], s[48:49], s[46:47]
	s_or_b64 s[44:45], s[46:47], s[44:45]
	v_cmp_lt_i32_e64 s[42:43], 58, v217
	v_cndmask_b32_e64 v68, 0, v68, s[44:45]
	v_cndmask_b32_e64 v94, 1.0, v94, s[44:45]
	v_cmp_lt_i32_e64 s[44:45], 59, v217
	v_cmp_lt_i32_e64 s[40:41], 57, v217
	s_or_b64 s[42:43], s[44:45], s[42:43]
	v_cmp_lt_i32_e64 s[38:39], 56, v217
	s_or_b64 s[40:41], s[42:43], s[40:41]
	v_cmp_lt_i32_e64 s[36:37], 51, v217
	s_or_b64 s[38:39], s[40:41], s[38:39]
	v_cmp_lt_i32_e64 s[34:35], 50, v217
	s_or_b64 s[36:37], s[38:39], s[36:37]
	v_cmp_lt_i32_e64 s[30:31], 49, v217
	s_or_b64 s[34:35], s[36:37], s[34:35]
	v_cmp_lt_i32_e64 s[28:29], 48, v217
	s_or_b64 s[30:31], s[34:35], s[30:31]
	v_cmp_lt_i32_e64 s[26:27], 43, v217
	s_or_b64 s[28:29], s[30:31], s[28:29]
	v_cmp_lt_i32_e64 s[24:25], 42, v217
	s_or_b64 s[26:27], s[28:29], s[26:27]
	v_cmp_lt_i32_e64 s[22:23], 41, v217
	s_or_b64 s[24:25], s[26:27], s[24:25]
	v_cmp_lt_i32_e64 s[20:21], 40, v217
	s_or_b64 s[22:23], s[24:25], s[22:23]
	v_cmp_lt_i32_e64 s[18:19], 35, v217
	s_or_b64 s[20:21], s[22:23], s[20:21]
	v_cmp_lt_i32_e64 s[16:17], 34, v217
	s_or_b64 s[18:19], s[20:21], s[18:19]
	v_cmp_lt_i32_e64 s[14:15], 33, v217
	s_or_b64 s[16:17], s[18:19], s[16:17]
	v_cmp_lt_i32_e32 vcc, 32, v217
	s_or_b64 s[14:15], s[16:17], s[14:15]
	s_or_b64 vcc, s[14:15], vcc
	v_cndmask_b32_e64 v173, 0, v173, s[74:75]
	v_cndmask_b32_e64 v172, 0, v172, s[72:73]
	v_cndmask_b32_e64 v81, 0, v81, s[70:71]
	v_cndmask_b32_e64 v80, 0, v80, s[68:69]
	v_cndmask_b32_e64 v79, 0, v79, s[66:67]
	v_cndmask_b32_e64 v78, 0, v78, s[64:65]
	v_cndmask_b32_e64 v77, 0, v77, s[62:63]
	v_cndmask_b32_e64 v76, 0, v76, s[60:61]
	v_cndmask_b32_e64 v75, 0, v75, s[58:59]
	v_cndmask_b32_e64 v74, 0, v74, s[56:57]
	v_cndmask_b32_e64 v73, 0, v73, s[54:55]
	v_cndmask_b32_e64 v72, 0, v72, s[52:53]
	v_cndmask_b32_e64 v71, 0, v71, s[50:51]
	v_cndmask_b32_e64 v70, 0, v70, s[48:49]
	v_cndmask_b32_e64 v69, 0, v69, s[46:47]
	v_cndmask_b32_e64 v95, 1.0, v95, s[46:47]
	v_cndmask_b32_e64 v96, 1.0, v96, s[48:49]
	v_cndmask_b32_e64 v97, 1.0, v97, s[50:51]
	v_cndmask_b32_e64 v98, 1.0, v98, s[52:53]
	v_cndmask_b32_e64 v99, 1.0, v99, s[54:55]
	v_cndmask_b32_e64 v170, 1.0, v170, s[56:57]
	v_cndmask_b32_e64 v171, 1.0, v171, s[58:59]
	v_cndmask_b32_e64 v174, 1.0, v174, s[60:61]
	v_cndmask_b32_e64 v175, 1.0, v175, s[62:63]
	v_cndmask_b32_e64 v82, 1.0, v82, s[64:65]
	v_cndmask_b32_e64 v83, 1.0, v83, s[66:67]
	v_cndmask_b32_e64 v178, 1.0, v178, s[68:69]
	v_cndmask_b32_e64 v179, 1.0, v179, s[70:71]
	v_cndmask_b32_e64 v180, 1.0, v180, s[72:73]
	v_cndmask_b32_e64 v181, 1.0, v181, s[74:75]
	v_cndmask_b32_e64 v183, 0, v183, s[44:45]
	v_cndmask_b32_e64 v182, 0, v182, s[42:43]
	v_cndmask_b32_e64 v177, 0, v177, s[40:41]
	v_cndmask_b32_e64 v176, 0, v176, s[38:39]
	v_cndmask_b32_e64 v169, 0, v169, s[36:37]
	v_cndmask_b32_e64 v168, 0, v168, s[34:35]
	v_cndmask_b32_e64 v93, 0, v93, s[30:31]
	v_cndmask_b32_e64 v92, 0, v92, s[28:29]
	v_cndmask_b32_e64 v91, 0, v91, s[26:27]
	v_cndmask_b32_e64 v90, 0, v90, s[24:25]
	v_cndmask_b32_e64 v89, 0, v89, s[22:23]
	v_cndmask_b32_e64 v88, 0, v88, s[20:21]
	v_cndmask_b32_e64 v87, 0, v87, s[18:19]
	v_cndmask_b32_e64 v86, 0, v86, s[16:17]
	v_cndmask_b32_e64 v85, 0, v85, s[14:15]
	v_cndmask_b32_e32 v84, 0, v84, vcc
	v_cndmask_b32_e32 v184, 1.0, v184, vcc
	v_cndmask_b32_e64 v185, 1.0, v185, s[14:15]
	v_cndmask_b32_e64 v186, 1.0, v186, s[16:17]
	v_cndmask_b32_e64 v187, 1.0, v187, s[18:19]
	v_cndmask_b32_e64 v188, 1.0, v188, s[20:21]
	v_cndmask_b32_e64 v189, 1.0, v189, s[22:23]
	v_cndmask_b32_e64 v190, 1.0, v190, s[24:25]
	v_cndmask_b32_e64 v191, 1.0, v191, s[26:27]
	v_cndmask_b32_e64 v192, 1.0, v192, s[28:29]
	v_cndmask_b32_e64 v193, 1.0, v193, s[30:31]
	v_cndmask_b32_e64 v194, 1.0, v194, s[34:35]
	v_cndmask_b32_e64 v195, 1.0, v195, s[36:37]
	v_cndmask_b32_e64 v196, 1.0, v196, s[38:39]
	v_cndmask_b32_e64 v197, 1.0, v197, s[40:41]
	v_cndmask_b32_e64 v198, 1.0, v198, s[42:43]
	v_cndmask_b32_e64 v199, 1.0, v199, s[44:45]

.LBB0_977:
	s_or_b64 exec, exec, s[2:3]
	s_add_i32 s0, s79, -1
	s_add_i32 s1, s6, 0x80
	s_cmp_lt_i32 s1, s88
	s_cselect_b64 s[2:3], -1, 0
	s_xor_b64 s[14:15], s[96:97], -1
	s_and_b64 s[14:15], s[2:3], s[14:15]
	s_and_saveexec_b64 s[2:3], s[14:15]
	s_cbranch_execz .LBB0_983
	s_add_i32 s4, s94, 0x8000
	s_and_b32 s4, s4, 0xc000
	s_add_i32 s7, s4, 0
	s_add_i32 s7, s7, 0x10000
	v_add_u32_e32 v2, s7, v206
	v_add_u32_e32 v76, v2, v207
	ds_read_b128 v[68:71], v76 offset:0
	ds_read_b128 v[72:75], v76 offset:0x2000
	v_add_u32_e32 v76, v2, v208
	ds_read_b128 v[132:135], v76 offset:0
	ds_read_b128 v[136:139], v76 offset:0x2000
	v_add_u32_e32 v76, v2, v209
	ds_read_b128 v[140:143], v76 offset:0
	ds_read_b128 v[144:147], v76 offset:0x2000
	v_add_u32_e32 v76, v2, v210
	ds_read_b128 v[148:151], v76 offset:0
	ds_read_b128 v[152:155], v76 offset:0x2000
	s_waitcnt lgkmcnt(4)
	s_add_i32 s1, s6, 0xbf
	s_cmp_lt_i32 s1, s78
	v_mfma_f32_32x32x16_bf16 v[84:99], v[68:71], v[124:127], 0
	v_mfma_f32_32x32x16_bf16 v[84:99], v[132:135], v[100:103], v[84:99]
	v_mfma_f32_32x32x16_bf16 v[68:83], v[72:75], v[124:127], 0
	v_mfma_f32_32x32x16_bf16 v[68:83], v[136:139], v[100:103], v[68:83]
	s_waitcnt lgkmcnt(0)
	v_mfma_f32_32x32x16_bf16 v[84:99], v[140:143], v[104:107], v[84:99]
	v_add_u32_e32 v140, v2, v212
	ds_read_b128 v[132:135], v140 offset:0
	ds_read_b128 v[136:139], v140 offset:0x2000
	v_add_u32_e32 v156, v2, v214
	v_mfma_f32_32x32x16_bf16 v[68:83], v[144:147], v[104:107], v[68:83]
	v_mfma_f32_32x32x16_bf16 v[84:99], v[148:151], v[108:111], v[84:99]
	v_add_u32_e32 v148, v2, v213
	ds_read_b128 v[140:143], v148 offset:0
	ds_read_b128 v[144:147], v148 offset:0x2000
	ds_read_b128 v[148:151], v156 offset:0
	v_add_u32_e32 v2, v2, v215
	v_mfma_f32_32x32x16_bf16 v[68:83], v[152:155], v[108:111], v[68:83]
	ds_read_b128 v[152:155], v156 offset:0x2000
	ds_read_b128 v[156:159], v2 offset:0
	ds_read_b128 v[160:163], v2 offset:0x2000
	s_waitcnt lgkmcnt(4)
	v_mfma_f32_32x32x16_bf16 v[84:99], v[132:135], v[112:115], v[84:99]
	v_mfma_f32_32x32x16_bf16 v[84:99], v[140:143], v[116:119], v[84:99]
	v_mfma_f32_32x32x16_bf16 v[68:83], v[136:139], v[112:115], v[68:83]
	v_mfma_f32_32x32x16_bf16 v[68:83], v[144:147], v[116:119], v[68:83]
	s_waitcnt lgkmcnt(0)
	v_mfma_f32_32x32x16_bf16 v[84:99], v[148:151], v[120:123], v[84:99]
	v_mfma_f32_32x32x16_bf16 v[84:99], v[156:159], v[128:131], v[84:99]
	v_mfma_f32_32x32x16_bf16 v[68:83], v[152:155], v[120:123], v[68:83]
	v_mfma_f32_32x32x16_bf16 v[68:83], v[160:163], v[128:131], v[68:83]
	v_add_u32_e32 v2, s4, v216
	ds_read_b64_tr_b16 v[160:161], v2 offset:0
	ds_read_b64_tr_b16 v[162:163], v2 offset:0x800
	ds_read_b64_tr_b16 v[156:157], v2 offset:0x1000
	ds_read_b64_tr_b16 v[158:159], v2 offset:0x1800
	ds_read_b64_tr_b16 v[152:153], v2 offset:0x2000
	ds_read_b64_tr_b16 v[154:155], v2 offset:0x2800
	ds_read_b64_tr_b16 v[148:149], v2 offset:0x3000
	ds_read_b64_tr_b16 v[150:151], v2 offset:0x3800
	ds_read_b64_tr_b16 v[144:145], v2 offset:0x200
	ds_read_b64_tr_b16 v[146:147], v2 offset:0xa00
	ds_read_b64_tr_b16 v[140:141], v2 offset:0x1200
	ds_read_b64_tr_b16 v[142:143], v2 offset:0x1a00
	ds_read_b64_tr_b16 v[136:137], v2 offset:0x2200
	ds_read_b64_tr_b16 v[138:139], v2 offset:0x2a00
	ds_read_b64_tr_b16 v[132:133], v2 offset:0x3200
	ds_read_b64_tr_b16 v[134:135], v2 offset:0x3a00
	s_nop 10
	v_max_f32_e64 v77, -v77, -v77
	v_min_f32_e32 v77, 0x42a00000, v77
	v_max_f32_e64 v82, -v82, -v82
	v_exp_f32_e32 v195, v77
	v_max_f32_e64 v77, -v94, -v94
	v_max_f32_e64 v78, -v78, -v78
	v_min_f32_e32 v82, 0x42a00000, v82
	v_min_f32_e32 v77, 0x42a00000, v77
	v_min_f32_e32 v78, 0x42a00000, v78
	v_exp_f32_e32 v228, v82
	v_max_f32_e64 v82, -v99, -v99
	v_exp_f32_e32 v196, v77
	v_exp_f32_e32 v198, v78
	v_max_f32_e64 v78, -v95, -v95
	v_max_f32_e64 v79, -v79, -v79
	v_min_f32_e32 v82, 0x42a00000, v82
	v_min_f32_e32 v78, 0x42a00000, v78
	v_min_f32_e32 v79, 0x42a00000, v79
	v_exp_f32_e32 v227, v82
	v_exp_f32_e32 v197, v78
	v_exp_f32_e32 v199, v79
	v_max_f32_e64 v79, -v96, -v96
	v_max_f32_e64 v80, -v80, -v80
	v_max_f32_e64 v84, -v84, -v84
	v_max_f32_e64 v69, -v69, -v69
	v_max_f32_e64 v70, -v70, -v70
	v_max_f32_e64 v71, -v71, -v71
	v_max_f32_e64 v72, -v72, -v72
	v_max_f32_e64 v73, -v73, -v73
	v_max_f32_e64 v74, -v74, -v74
	v_max_f32_e64 v75, -v75, -v75
	v_max_f32_e64 v76, -v76, -v76
	v_min_f32_e32 v79, 0x42a00000, v79
	v_min_f32_e32 v80, 0x42a00000, v80
	v_min_f32_e32 v84, 0x42a00000, v84
	v_min_f32_e32 v69, 0x42a00000, v69
	v_min_f32_e32 v70, 0x42a00000, v70
	v_min_f32_e32 v71, 0x42a00000, v71
	v_min_f32_e32 v72, 0x42a00000, v72
	v_min_f32_e32 v73, 0x42a00000, v73
	v_min_f32_e32 v74, 0x42a00000, v74
	v_min_f32_e32 v75, 0x42a00000, v75
	v_min_f32_e32 v76, 0x42a00000, v76
	v_add_f32_e32 v94, 1.0, v196
	v_exp_f32_e32 v222, v79
	v_exp_f32_e32 v224, v80
	v_max_f32_e64 v80, -v97, -v97
	v_max_f32_e64 v81, -v81, -v81
	v_add_f32_e32 v82, 1.0, v228
	v_exp_f32_e32 v170, v84
	v_max_f32_e64 v84, -v85, -v85
	v_exp_f32_e32 v185, v69
	v_max_f32_e64 v69, -v86, -v86
	v_exp_f32_e32 v186, v70
	v_max_f32_e64 v70, -v87, -v87
	v_exp_f32_e32 v187, v71
	v_max_f32_e64 v71, -v88, -v88
	v_exp_f32_e32 v188, v72
	v_max_f32_e64 v72, -v89, -v89
	v_exp_f32_e32 v189, v73
	v_max_f32_e64 v73, -v90, -v90
	v_exp_f32_e32 v190, v74
	v_max_f32_e64 v74, -v91, -v91
	v_exp_f32_e32 v191, v75
	v_max_f32_e64 v75, -v92, -v92
	v_exp_f32_e32 v194, v76
	v_max_f32_e64 v76, -v93, -v93
	v_rcp_f32_e32 v78, v94
	v_add_f32_e32 v94, 1.0, v198
	v_min_f32_e32 v80, 0x42a00000, v80
	v_min_f32_e32 v81, 0x42a00000, v81
	v_rcp_f32_e32 v182, v82
	v_add_f32_e32 v82, 1.0, v227
	v_max_f32_e64 v68, -v68, -v68
	v_min_f32_e32 v84, 0x42a00000, v84
	v_min_f32_e32 v69, 0x42a00000, v69
	v_min_f32_e32 v70, 0x42a00000, v70
	v_min_f32_e32 v71, 0x42a00000, v71
	v_min_f32_e32 v72, 0x42a00000, v72
	v_min_f32_e32 v73, 0x42a00000, v73
	v_min_f32_e32 v74, 0x42a00000, v74
	v_min_f32_e32 v75, 0x42a00000, v75
	v_min_f32_e32 v76, 0x42a00000, v76
	v_rcp_f32_e32 v168, v94
	v_add_f32_e32 v94, 1.0, v197
	v_exp_f32_e32 v223, v80
	v_exp_f32_e32 v225, v81
	v_max_f32_e64 v81, -v98, -v98
	v_rcp_f32_e32 v173, v82
	v_max_f32_e64 v82, -v83, -v83
	v_min_f32_e32 v68, 0x42a00000, v68
	v_exp_f32_e32 v171, v84
	v_exp_f32_e32 v174, v69
	v_exp_f32_e32 v175, v70
	v_exp_f32_e32 v178, v71
	v_exp_f32_e32 v179, v72
	v_exp_f32_e32 v180, v73
	v_exp_f32_e32 v181, v74
	v_exp_f32_e32 v192, v75
	v_exp_f32_e32 v193, v76
	v_rcp_f32_e32 v79, v94
	v_add_f32_e32 v94, 1.0, v199
	v_min_f32_e32 v81, 0x42a00000, v81
	v_min_f32_e32 v82, 0x42a00000, v82
	v_exp_f32_e32 v184, v68
	v_rcp_f32_e32 v169, v94
	v_add_f32_e32 v94, 1.0, v222
	v_exp_f32_e32 v226, v81
	v_exp_f32_e32 v229, v82
	v_rcp_f32_e32 v80, v94
	v_add_f32_e32 v94, 1.0, v224
	v_rcp_f32_e32 v176, v94
	v_add_f32_e32 v94, 1.0, v223
	v_add_f32_e32 v85, 1.0, v171
	v_add_f32_e32 v86, 1.0, v174
	v_add_f32_e32 v87, 1.0, v175
	v_add_f32_e32 v88, 1.0, v178
	v_add_f32_e32 v89, 1.0, v179
	v_add_f32_e32 v90, 1.0, v180
	v_add_f32_e32 v91, 1.0, v181
	v_add_f32_e32 v92, 1.0, v192
	v_add_f32_e32 v93, 1.0, v193
	v_rcp_f32_e32 v81, v94
	v_add_f32_e32 v94, 1.0, v225
	v_add_f32_e32 v68, 1.0, v170
	v_add_f32_e32 v84, 1.0, v184
	v_rcp_f32_e32 v69, v85
	v_add_f32_e32 v85, 1.0, v185
	v_rcp_f32_e32 v70, v86
	v_add_f32_e32 v86, 1.0, v186
	v_rcp_f32_e32 v71, v87
	v_add_f32_e32 v87, 1.0, v187
	v_rcp_f32_e32 v72, v88
	v_add_f32_e32 v88, 1.0, v188
	v_rcp_f32_e32 v73, v89
	v_add_f32_e32 v89, 1.0, v189
	v_rcp_f32_e32 v74, v90
	v_add_f32_e32 v90, 1.0, v190
	v_rcp_f32_e32 v75, v91
	v_add_f32_e32 v91, 1.0, v191
	v_rcp_f32_e32 v76, v92
	v_add_f32_e32 v92, 1.0, v194
	v_rcp_f32_e32 v77, v93
	v_add_f32_e32 v93, 1.0, v195
	v_rcp_f32_e32 v177, v94
	v_add_f32_e32 v94, 1.0, v226
	v_add_f32_e32 v183, 1.0, v229
	v_rcp_f32_e32 v68, v68
	v_rcp_f32_e32 v84, v84
	v_rcp_f32_e32 v85, v85
	v_rcp_f32_e32 v86, v86
	v_rcp_f32_e32 v87, v87
	v_rcp_f32_e32 v88, v88
	v_rcp_f32_e32 v89, v89
	v_rcp_f32_e32 v90, v90
	v_rcp_f32_e32 v91, v91
	v_rcp_f32_e32 v92, v92
	v_rcp_f32_e32 v93, v93
	v_rcp_f32_e32 v172, v94
	v_rcp_f32_e32 v183, v183
	v_pk_mul_f32 v[94:95], v[170:171], v[68:69]
	v_pk_mul_f32 v[96:97], v[174:175], v[70:71]
	v_pk_mul_f32 v[98:99], v[178:179], v[72:73]
	v_pk_mul_f32 v[170:171], v[180:181], v[74:75]
	v_pk_mul_f32 v[174:175], v[192:193], v[76:77]
	v_pk_mul_f32 v[82:83], v[196:197], v[78:79]
	v_pk_mul_f32 v[178:179], v[222:223], v[80:81]
	v_pk_mul_f32 v[180:181], v[226:227], v[172:173]
	v_pk_mul_f32 v[184:185], v[184:185], v[84:85]
	v_pk_mul_f32 v[186:187], v[186:187], v[86:87]
	v_pk_mul_f32 v[188:189], v[188:189], v[88:89]
	v_pk_mul_f32 v[190:191], v[190:191], v[90:91]
	v_pk_mul_f32 v[192:193], v[194:195], v[92:93]
	v_pk_mul_f32 v[194:195], v[198:199], v[168:169]
	v_pk_mul_f32 v[196:197], v[224:225], v[176:177]
	v_pk_mul_f32 v[198:199], v[228:229], v[182:183]
	s_cbranch_scc1 .LBB0_980
	v_add_u32_e32 v221, 64, v217
	v_cmp_lt_i32_e64 s[72:73], 26, v221
	v_cmp_lt_i32_e64 s[74:75], 27, v221
	v_cmp_lt_i32_e64 s[70:71], 25, v221
	s_or_b64 s[72:73], s[74:75], s[72:73]
	v_cmp_lt_i32_e64 s[68:69], 24, v221
	s_or_b64 s[70:71], s[72:73], s[70:71]
	v_cmp_lt_i32_e64 s[66:67], 19, v221
	s_or_b64 s[68:69], s[70:71], s[68:69]
	v_cmp_lt_i32_e64 s[64:65], 18, v221
	s_or_b64 s[66:67], s[68:69], s[66:67]
	v_cmp_lt_i32_e64 s[62:63], 17, v221
	s_or_b64 s[64:65], s[66:67], s[64:65]
	v_cmp_lt_i32_e64 s[60:61], 16, v221
	s_or_b64 s[62:63], s[64:65], s[62:63]
	v_cmp_lt_i32_e64 s[58:59], 11, v221
	s_or_b64 s[60:61], s[62:63], s[60:61]
	v_cmp_lt_i32_e64 s[56:57], 10, v221
	s_or_b64 s[58:59], s[60:61], s[58:59]
	v_cmp_lt_i32_e64 s[54:55], 9, v221
	s_or_b64 s[56:57], s[58:59], s[56:57]
	v_cmp_lt_i32_e64 s[52:53], 8, v221
	s_or_b64 s[54:55], s[56:57], s[54:55]
	v_cmp_lt_i32_e64 s[50:51], 3, v221
	s_or_b64 s[52:53], s[54:55], s[52:53]
	v_cmp_lt_i32_e64 s[48:49], 2, v221
	s_or_b64 s[50:51], s[52:53], s[50:51]
	v_cmp_lt_i32_e64 s[46:47], 1, v221
	s_or_b64 s[48:49], s[50:51], s[48:49]
	v_cmp_lt_i32_e64 s[44:45], 0, v221
	s_or_b64 s[46:47], s[48:49], s[46:47]
	s_or_b64 s[44:45], s[46:47], s[44:45]
	v_cmp_lt_i32_e64 s[42:43], 58, v221
	v_cndmask_b32_e64 v68, 0, v68, s[44:45]
	v_cndmask_b32_e64 v94, 1.0, v94, s[44:45]
	v_cmp_lt_i32_e64 s[44:45], 59, v221
	v_cmp_lt_i32_e64 s[40:41], 57, v221
	s_or_b64 s[42:43], s[44:45], s[42:43]
	v_cmp_lt_i32_e64 s[38:39], 56, v221
	s_or_b64 s[40:41], s[42:43], s[40:41]
	v_cmp_lt_i32_e64 s[36:37], 51, v221
	s_or_b64 s[38:39], s[40:41], s[38:39]
	v_cmp_lt_i32_e64 s[34:35], 50, v221
	s_or_b64 s[36:37], s[38:39], s[36:37]
	v_cmp_lt_i32_e64 s[30:31], 49, v221
	s_or_b64 s[34:35], s[36:37], s[34:35]
	v_cmp_lt_i32_e64 s[28:29], 48, v221
	s_or_b64 s[30:31], s[34:35], s[30:31]
	v_cmp_lt_i32_e64 s[26:27], 43, v221
	s_or_b64 s[28:29], s[30:31], s[28:29]
	v_cmp_lt_i32_e64 s[24:25], 42, v221
	s_or_b64 s[26:27], s[28:29], s[26:27]
	v_cmp_lt_i32_e64 s[22:23], 41, v221
	s_or_b64 s[24:25], s[26:27], s[24:25]
	v_cmp_lt_i32_e64 s[20:21], 40, v221
	s_or_b64 s[22:23], s[24:25], s[22:23]
	v_cmp_lt_i32_e64 s[18:19], 35, v221
	s_or_b64 s[20:21], s[22:23], s[20:21]
	v_cmp_lt_i32_e64 s[16:17], 34, v221
	s_or_b64 s[18:19], s[20:21], s[18:19]
	v_cmp_lt_i32_e64 s[14:15], 33, v221
	s_or_b64 s[16:17], s[18:19], s[16:17]
	v_cmp_lt_i32_e32 vcc, 32, v221
	s_or_b64 s[14:15], s[16:17], s[14:15]
	s_or_b64 vcc, s[14:15], vcc
	v_cndmask_b32_e64 v173, 0, v173, s[74:75]
	v_cndmask_b32_e64 v172, 0, v172, s[72:73]
	v_cndmask_b32_e64 v81, 0, v81, s[70:71]
	v_cndmask_b32_e64 v80, 0, v80, s[68:69]
	v_cndmask_b32_e64 v79, 0, v79, s[66:67]
	v_cndmask_b32_e64 v78, 0, v78, s[64:65]
	v_cndmask_b32_e64 v77, 0, v77, s[62:63]
	v_cndmask_b32_e64 v76, 0, v76, s[60:61]
	v_cndmask_b32_e64 v75, 0, v75, s[58:59]
	v_cndmask_b32_e64 v74, 0, v74, s[56:57]
	v_cndmask_b32_e64 v73, 0, v73, s[54:55]
	v_cndmask_b32_e64 v72, 0, v72, s[52:53]
	v_cndmask_b32_e64 v71, 0, v71, s[50:51]
	v_cndmask_b32_e64 v70, 0, v70, s[48:49]
	v_cndmask_b32_e64 v69, 0, v69, s[46:47]
	v_cndmask_b32_e64 v95, 1.0, v95, s[46:47]
	v_cndmask_b32_e64 v96, 1.0, v96, s[48:49]
	v_cndmask_b32_e64 v97, 1.0, v97, s[50:51]
	v_cndmask_b32_e64 v98, 1.0, v98, s[52:53]
	v_cndmask_b32_e64 v99, 1.0, v99, s[54:55]
	v_cndmask_b32_e64 v170, 1.0, v170, s[56:57]
	v_cndmask_b32_e64 v171, 1.0, v171, s[58:59]
	v_cndmask_b32_e64 v174, 1.0, v174, s[60:61]
	v_cndmask_b32_e64 v175, 1.0, v175, s[62:63]
	v_cndmask_b32_e64 v82, 1.0, v82, s[64:65]
	v_cndmask_b32_e64 v83, 1.0, v83, s[66:67]
	v_cndmask_b32_e64 v178, 1.0, v178, s[68:69]
	v_cndmask_b32_e64 v179, 1.0, v179, s[70:71]
	v_cndmask_b32_e64 v180, 1.0, v180, s[72:73]
	v_cndmask_b32_e64 v181, 1.0, v181, s[74:75]
	v_cndmask_b32_e64 v183, 0, v183, s[44:45]
	v_cndmask_b32_e64 v182, 0, v182, s[42:43]
	v_cndmask_b32_e64 v177, 0, v177, s[40:41]
	v_cndmask_b32_e64 v176, 0, v176, s[38:39]
	v_cndmask_b32_e64 v169, 0, v169, s[36:37]
	v_cndmask_b32_e64 v168, 0, v168, s[34:35]
	v_cndmask_b32_e64 v93, 0, v93, s[30:31]
	v_cndmask_b32_e64 v92, 0, v92, s[28:29]
	v_cndmask_b32_e64 v91, 0, v91, s[26:27]
	v_cndmask_b32_e64 v90, 0, v90, s[24:25]
	v_cndmask_b32_e64 v89, 0, v89, s[22:23]
	v_cndmask_b32_e64 v88, 0, v88, s[20:21]
	v_cndmask_b32_e64 v87, 0, v87, s[18:19]
	v_cndmask_b32_e64 v86, 0, v86, s[16:17]
	v_cndmask_b32_e64 v85, 0, v85, s[14:15]
	v_cndmask_b32_e32 v84, 0, v84, vcc
	v_cndmask_b32_e32 v184, 1.0, v184, vcc
	v_cndmask_b32_e64 v185, 1.0, v185, s[14:15]
	v_cndmask_b32_e64 v186, 1.0, v186, s[16:17]
	v_cndmask_b32_e64 v187, 1.0, v187, s[18:19]
	v_cndmask_b32_e64 v188, 1.0, v188, s[20:21]
	v_cndmask_b32_e64 v189, 1.0, v189, s[22:23]
	v_cndmask_b32_e64 v190, 1.0, v190, s[24:25]
	v_cndmask_b32_e64 v191, 1.0, v191, s[26:27]
	v_cndmask_b32_e64 v192, 1.0, v192, s[28:29]
	v_cndmask_b32_e64 v193, 1.0, v193, s[30:31]
	v_cndmask_b32_e64 v194, 1.0, v194, s[34:35]
	v_cndmask_b32_e64 v195, 1.0, v195, s[36:37]
	v_cndmask_b32_e64 v196, 1.0, v196, s[38:39]
	v_cndmask_b32_e64 v197, 1.0, v197, s[40:41]
	v_cndmask_b32_e64 v198, 1.0, v198, s[42:43]
	v_cndmask_b32_e64 v199, 1.0, v199, s[44:45]
